# loop-edge edit: K-loop pointer-update and next-tile-select SALU (14 instrs) moved from the head of the first load segment into the last compute segment, one per MFMA (up-GEMM and QKV/conv-in GEMM loop
# baseline (speedup 1.0000x reference)
; #define PG8_STAGE(bufoff, gbase, voff) do { _Pragma("unroll") for (int _i = 0; _i < 2; ++_i) \
;         __builtin_amdgcn_global_load_lds((const unsigned*)((const char*)(gbase) + (voff)[_i]), (PG8_LAS unsigned*)(lds + (bufoff) + ldsw + _i * 8192), 16, 0, 0); } while (0)
; #define PG8_LDA(dst, b, h) do { _Pragma("unroll") for (int m = 0; m < 4; ++m) _Pragma("unroll") for (int k = 0; k < 2; ++k) dst[m][k] = *(const PG8_LAS bf16x8*)(lds + PG8_SA(b, h) + aoff + m * 2048 + k * 1024); } while (0)
; #define PG8_LDB(dst, b, h) do { _Pragma("unroll") for (int n = 0; n < 2; ++n) _Pragma("unroll") for (int k = 0; k < 2; ++k) dst[n][k] = *(const PG8_LAS bf16x8*)(lds + PG8_SB(b, h) + boff + n * 2048 + k * 1024); } while (0)
; #define PG8_SCHED __builtin_amdgcn_sched_barrier(0)
; template <class Epi, class Sched, bool ALIGN_EPI = false, bool SP2 = false>
; __device__ __forceinline__ void gemm_phase(PG8_LAS unsigned char* lds, const Gemm g, const Sched& S, const Epi& E) {
;     ...
;         const bool has_next = S.next(ui + 1, nxt);
;         const char* nA = has_next ? (const char*)g.A + (size_t)nxt.pm * tstep : cA; const char* nB = has_next ? (const char*)g.Bt + (size_t)nxt.pn * tstep : cB;
;         for (int t = 0; t < nt; t += 2) {
;             const bool last = (t == nt - 2);
;             const char* a1 = cA + (size_t)(t + 1) * kstep;
;             const char* a2 = last ? nA : cA + (size_t)(t + 2) * kstep; const char* b2 = last ? nB : cB + (size_t)(t + 2) * kstep;
;             const char* a3 = a2 + kstep; const char* b3 = b2 + kstep;
;             if (last && has_next) S.a_ready(nxt);
;             if constexpr (SP2) {
;             PG8_LDB(B0, 0, 0); PG8_LDB(B1, 0, 1); PG8_SCHED; PG8_LDA(At, 0, 0); PG8_STAGE(PG8_SA(1, 1), a1 + hstep, voffA);
;     ...
; #pragma unroll
;         for (int a = 0; a < 2; ++a)
; #pragma unroll
;             for (int b = 0; b < 2; ++b)
; #pragma unroll
;                 for (int m = 0; m < 4; ++m)
; #pragma unroll
;                     for (int n = 0; n < 2; ++n) acc[a][b][m][n] = (f32x4){0.f, 0.f, 0.f, 0.f};
;         cur = nxt; cA = nA; cB = nB; ++ui;
.LBB0_54:
	s_ashr_i32 s27, s26, 31
	s_lshl_b64 s[28:29], s[26:27], 20
	s_add_u32 s36, s74, s28
	s_addc_u32 s37, s75, s29
	s_and_b64 s[28:29], s[40:41], exec
	s_cselect_b32 s27, s37, s43
	s_cselect_b32 s65, s36, s42
	s_ashr_i32 s25, s24, 31
	s_lshl_b64 s[28:29], s[24:25], 20
	s_add_u32 s38, s2, s28
	s_addc_u32 s39, s7, s29
	s_and_b64 s[28:29], s[40:41], exec
	s_cselect_b32 s25, s39, s51
	s_cselect_b32 s66, s38, s50
	s_add_u32 s42, s42, 0x80080
	s_addc_u32 s43, s43, 0
	s_add_u32 s67, s50, 0x100
	v_mov_b32_e32 v0, 0
	s_addc_u32 s70, s51, 0
	s_mov_b32 s71, -2
	v_mov_b32_e32 v1, v0
	v_mov_b32_e32 v2, v0
	v_mov_b32_e32 v3, v0
	v_mov_b32_e32 v4, v0
	v_mov_b32_e32 v5, v0
	v_mov_b32_e32 v6, v0
	v_mov_b32_e32 v7, v0
	v_mov_b32_e32 v16, v0
	v_mov_b32_e32 v17, v0
	v_mov_b32_e32 v18, v0
	v_mov_b32_e32 v19, v0
	v_mov_b32_e32 v20, v0
	v_mov_b32_e32 v21, v0
	v_mov_b32_e32 v22, v0
	v_mov_b32_e32 v23, v0
	v_mov_b32_e32 v32, v0
	v_mov_b32_e32 v33, v0
	v_mov_b32_e32 v34, v0
	v_mov_b32_e32 v35, v0
	v_mov_b32_e32 v36, v0
	v_mov_b32_e32 v37, v0
	v_mov_b32_e32 v38, v0
	v_mov_b32_e32 v39, v0
	v_mov_b32_e32 v48, v0
	v_mov_b32_e32 v49, v0
	v_mov_b32_e32 v50, v0
	v_mov_b32_e32 v51, v0
	v_mov_b32_e32 v52, v0
	v_mov_b32_e32 v53, v0
	v_mov_b32_e32 v54, v0
	v_mov_b32_e32 v55, v0
	v_mov_b32_e32 v8, v0
	v_mov_b32_e32 v9, v0
	v_mov_b32_e32 v10, v0
	v_mov_b32_e32 v11, v0
	v_mov_b32_e32 v12, v0
	v_mov_b32_e32 v13, v0
	v_mov_b32_e32 v14, v0
	v_mov_b32_e32 v15, v0
	v_mov_b32_e32 v24, v0
	v_mov_b32_e32 v25, v0
	v_mov_b32_e32 v26, v0
	v_mov_b32_e32 v27, v0
	v_mov_b32_e32 v28, v0
	v_mov_b32_e32 v29, v0
	v_mov_b32_e32 v30, v0
	v_mov_b32_e32 v31, v0
	v_mov_b32_e32 v40, v0
	v_mov_b32_e32 v41, v0
	v_mov_b32_e32 v42, v0
	v_mov_b32_e32 v43, v0
	v_mov_b32_e32 v44, v0
	v_mov_b32_e32 v45, v0
	v_mov_b32_e32 v46, v0
	v_mov_b32_e32 v47, v0
	v_mov_b32_e32 v56, v0
	v_mov_b32_e32 v57, v0
	v_mov_b32_e32 v58, v0
	v_mov_b32_e32 v59, v0
	v_mov_b32_e32 v60, v0
	v_mov_b32_e32 v61, v0
	v_mov_b32_e32 v62, v0
	v_mov_b32_e32 v63, v0
	v_mov_b32_e32 v80, v0
	v_mov_b32_e32 v81, v0
	v_mov_b32_e32 v82, v0
	v_mov_b32_e32 v83, v0
	v_mov_b32_e32 v84, v0
	v_mov_b32_e32 v85, v0
	v_mov_b32_e32 v86, v0
	v_mov_b32_e32 v87, v0
	v_mov_b32_e32 v96, v0
	v_mov_b32_e32 v97, v0
	v_mov_b32_e32 v98, v0
	v_mov_b32_e32 v99, v0
	v_mov_b32_e32 v100, v0
	v_mov_b32_e32 v101, v0
	v_mov_b32_e32 v102, v0
	v_mov_b32_e32 v103, v0
	v_mov_b32_e32 v112, v0
	v_mov_b32_e32 v113, v0
	v_mov_b32_e32 v114, v0
	v_mov_b32_e32 v115, v0
	v_mov_b32_e32 v116, v0
	v_mov_b32_e32 v117, v0
	v_mov_b32_e32 v118, v0
	v_mov_b32_e32 v119, v0
	v_mov_b32_e32 v128, v0
	v_mov_b32_e32 v129, v0
	v_mov_b32_e32 v130, v0
	v_mov_b32_e32 v131, v0
	v_mov_b32_e32 v132, v0
	v_mov_b32_e32 v133, v0
	v_mov_b32_e32 v134, v0
	v_mov_b32_e32 v135, v0
	v_mov_b32_e32 v88, v0
	v_mov_b32_e32 v89, v0
	v_mov_b32_e32 v90, v0
	v_mov_b32_e32 v91, v0
	v_mov_b32_e32 v92, v0
	v_mov_b32_e32 v93, v0
	v_mov_b32_e32 v94, v0
	v_mov_b32_e32 v95, v0
	v_mov_b32_e32 v104, v0
	v_mov_b32_e32 v105, v0
	v_mov_b32_e32 v106, v0
	v_mov_b32_e32 v107, v0
	v_mov_b32_e32 v108, v0
	v_mov_b32_e32 v109, v0
	v_mov_b32_e32 v110, v0
	v_mov_b32_e32 v111, v0
	v_mov_b32_e32 v120, v0
	v_mov_b32_e32 v121, v0
	v_mov_b32_e32 v122, v0
	v_mov_b32_e32 v123, v0
	v_mov_b32_e32 v124, v0
	v_mov_b32_e32 v125, v0
	v_mov_b32_e32 v126, v0
	v_mov_b32_e32 v127, v0
	v_mov_b32_e32 v136, v0
	v_mov_b32_e32 v137, v0
	v_mov_b32_e32 v138, v0
	v_mov_b32_e32 v139, v0
	v_mov_b32_e32 v140, v0
	v_mov_b32_e32 v141, v0
	v_mov_b32_e32 v142, v0
	v_mov_b32_e32 v143, v0
	s_nop 0
	s_nop 0
	s_nop 0
	s_nop 0
	s_nop 0
	s_nop 0
	s_nop 0
	s_nop 0
	v_add_u32_e32 v192, 0x10000, v163
	v_add_u32_e32 v193, 0x14000, v163
	v_add_u32_e32 v212, 0x18000, v163
	v_add_u32_e32 v213, 0x1c000, v163
	s_add_u32 s28, s42, 0xfff80080
	s_addc_u32 s29, s43, -1
	s_add_i32 s72, 0, 0x10000
	s_cmp_eq_u32 s71, 28
	s_cselect_b32 s53, s27, s29
	s_cselect_b32 s52, s65, s28
	s_cselect_b32 s51, s25, s70
	s_cselect_b32 s50, s66, s67
	s_add_i32 s73, 0, 0x14000
.LBB0_55:
	ds_read_b128 v[64:67], v192
	ds_read_b128 v[68:71], v192 offset:1024
	ds_read_b128 v[72:75], v192 offset:2048
	ds_read_b128 v[76:79], v192 offset:3072
	ds_read_b128 v[156:159], v193
	ds_read_b128 v[168:171], v193 offset:1024
	ds_read_b128 v[172:175], v193 offset:2048
	ds_read_b128 v[176:179], v193 offset:3072
	s_add_i32 m0, s12, 0xc000
	ds_read_b128 v[180:183], v165
	ds_read_b128 v[184:187], v165 offset:1024
	ds_read_b128 v[188:191], v165 offset:2048
	ds_read_b128 v[196:199], v165 offset:3072
	ds_read_b128 v[200:203], v165 offset:4096
	ds_read_b128 v[204:207], v165 offset:5120
	ds_read_b128 v[208:211], v165 offset:6144
	ds_read_b128 v[222:225], v165 offset:7168
	global_load_lds_dwordx4 v152, s[42:43]
	s_add_i32 m0, s12, 0xe000
	s_nop 0
	global_load_lds_dwordx4 v154, s[42:43]
	s_waitcnt vmcnt(8)
	s_waitcnt lgkmcnt(0)
	s_barrier
; #define PG8_STAGE(bufoff, gbase, voff) do { _Pragma("unroll") for (int _i = 0; _i < 2; ++_i) \
;         __builtin_amdgcn_global_load_lds((const unsigned*)((const char*)(gbase) + (voff)[_i]), (PG8_LAS unsigned*)(lds + (bufoff) + ldsw + _i * 8192), 16, 0, 0); } while (0)
; #define PG8_LDA(dst, b, h) do { _Pragma("unroll") for (int m = 0; m < 4; ++m) _Pragma("unroll") for (int k = 0; k < 2; ++k) dst[m][k] = *(const PG8_LAS bf16x8*)(lds + PG8_SA(b, h) + aoff + m * 2048 + k * 1024); } while (0)
; #define PG8_LDB(dst, b, h) do { _Pragma("unroll") for (int n = 0; n < 2; ++n) _Pragma("unroll") for (int k = 0; k < 2; ++k) dst[n][k] = *(const PG8_LAS bf16x8*)(lds + PG8_SB(b, h) + boff + n * 2048 + k * 1024); } while (0)
; #define PG8_MMA(ai, bj, At, Bt) do { __builtin_amdgcn_s_setprio(1); _Pragma("unroll") for (int m = 0; m < 4; ++m) _Pragma("unroll") for (int n = 0; n < 2; ++n) _Pragma("unroll") for (int k = 0; k < 2; ++k) \
;         acc[ai][bj][m][n] = __builtin_amdgcn_mfma_f32_16x16x32_bf16(Bt[n][k], At[m][k], acc[ai][bj][m][n], 0, 0, 0); __builtin_amdgcn_s_setprio(0); } while (0)
; #define PG8_WAIT_V(n) asm volatile("s_waitcnt vmcnt(" #n ")" ::: "memory")
; #define PG8_WAIT_L(n) asm volatile("s_waitcnt lgkmcnt(" #n ")" ::: "memory")
; #define PG8_BAR __builtin_amdgcn_s_barrier()
; #define PG8_SCHED __builtin_amdgcn_sched_barrier(0)
; template <class Epi, class Sched, bool ALIGN_EPI = false, bool SP2 = false>
; __device__ __forceinline__ void gemm_phase(PG8_LAS unsigned char* lds, const Gemm g, const Sched& S, const Epi& E) {
;     ...
;             PG8_LDB(B0, 0, 0); PG8_LDB(B1, 0, 1); PG8_SCHED; PG8_LDA(At, 0, 0); PG8_STAGE(PG8_SA(1, 1), a1 + hstep, voffA);
;             PG8_WAIT_V(8); PG8_WAIT_L(0); PG8_BAR; PG8_MMA(0, 0, At, B0); PG8_MMA(0, 1, At, B1); PG8_BAR; PG8_SCHED;
;             PG8_LDA(At, 0, 1); PG8_STAGE(PG8_SB(0, 0), b2, voffB); PG8_STAGE(PG8_SB(0, 1), b2 + hstep, voffB); PG8_STAGE(PG8_SA(0, 0), a2, voffA);
;             PG8_WAIT_V(8); PG8_WAIT_L(0); PG8_BAR; PG8_MMA(1, 0, At, B0); PG8_MMA(1, 1, At, B1); PG8_BAR; PG8_SCHED;
	s_setprio 1
	s_waitcnt lgkmcnt(0)
	v_mfma_f32_16x16x32_bf16 v[140:143], v[64:67], v[180:183], v[140:143]
	v_mfma_f32_16x16x32_bf16 v[136:139], v[72:75], v[180:183], v[136:139]
	v_mfma_f32_16x16x32_bf16 v[124:127], v[64:67], v[188:191], v[124:127]
	v_mfma_f32_16x16x32_bf16 v[120:123], v[72:75], v[188:191], v[120:123]
	v_mfma_f32_16x16x32_bf16 v[108:111], v[64:67], v[200:203], v[108:111]
	v_mfma_f32_16x16x32_bf16 v[104:107], v[72:75], v[200:203], v[104:107]
	v_mfma_f32_16x16x32_bf16 v[92:95], v[64:67], v[208:211], v[92:95]
	v_mfma_f32_16x16x32_bf16 v[88:91], v[72:75], v[208:211], v[88:91]
	v_mfma_f32_16x16x32_bf16 v[140:143], v[68:71], v[184:187], v[140:143]
	v_mfma_f32_16x16x32_bf16 v[136:139], v[76:79], v[184:187], v[136:139]
	v_mfma_f32_16x16x32_bf16 v[124:127], v[68:71], v[196:199], v[124:127]
	v_mfma_f32_16x16x32_bf16 v[120:123], v[76:79], v[196:199], v[120:123]
	v_mfma_f32_16x16x32_bf16 v[108:111], v[68:71], v[204:207], v[108:111]
	v_mfma_f32_16x16x32_bf16 v[104:107], v[76:79], v[204:207], v[104:107]
	v_mfma_f32_16x16x32_bf16 v[92:95], v[68:71], v[222:225], v[92:95]
	v_mfma_f32_16x16x32_bf16 v[88:91], v[76:79], v[222:225], v[88:91]
	s_setprio 0
	s_setprio 1
	v_mfma_f32_16x16x32_bf16 v[132:135], v[156:159], v[180:183], v[132:135]
	v_mfma_f32_16x16x32_bf16 v[128:131], v[172:175], v[180:183], v[128:131]
	v_mfma_f32_16x16x32_bf16 v[116:119], v[156:159], v[188:191], v[116:119]
	v_mfma_f32_16x16x32_bf16 v[112:115], v[172:175], v[188:191], v[112:115]
	v_mfma_f32_16x16x32_bf16 v[100:103], v[156:159], v[200:203], v[100:103]
	v_mfma_f32_16x16x32_bf16 v[96:99], v[172:175], v[200:203], v[96:99]
	v_mfma_f32_16x16x32_bf16 v[84:87], v[156:159], v[208:211], v[84:87]
	v_mfma_f32_16x16x32_bf16 v[80:83], v[172:175], v[208:211], v[80:83]
	v_mfma_f32_16x16x32_bf16 v[132:135], v[168:171], v[184:187], v[132:135]
	v_mfma_f32_16x16x32_bf16 v[128:131], v[176:179], v[184:187], v[128:131]
	v_mfma_f32_16x16x32_bf16 v[116:119], v[168:171], v[196:199], v[116:119]
	v_mfma_f32_16x16x32_bf16 v[112:115], v[176:179], v[196:199], v[112:115]
	v_mfma_f32_16x16x32_bf16 v[100:103], v[168:171], v[204:207], v[100:103]
	v_mfma_f32_16x16x32_bf16 v[96:99], v[176:179], v[204:207], v[96:99]
	v_mfma_f32_16x16x32_bf16 v[84:87], v[168:171], v[222:225], v[84:87]
	v_mfma_f32_16x16x32_bf16 v[80:83], v[176:179], v[222:225], v[80:83]
	s_setprio 0
	s_barrier
	s_add_i32 s28, s72, s8
	s_mov_b32 m0, s28
	ds_read_b128 v[180:183], v165 offset:16384
	ds_read_b128 v[184:187], v165 offset:17408
	ds_read_b128 v[188:191], v165 offset:18432
	ds_read_b128 v[196:199], v165 offset:19456
	ds_read_b128 v[200:203], v165 offset:20480
	ds_read_b128 v[204:207], v165 offset:21504
	ds_read_b128 v[208:211], v165 offset:22528
	ds_read_b128 v[222:225], v165 offset:23552
	global_load_lds_dwordx4 v194, s[50:51]
	s_add_i32 m0, s28, 0x2000
	s_add_u32 s28, s50, 0x80000
	s_addc_u32 s29, s51, 0
	s_add_i32 s72, s73, s8
	global_load_lds_dwordx4 v144, s[50:51]
	s_mov_b32 m0, s72
	s_nop 0
	global_load_lds_dwordx4 v194, s[28:29]
	s_add_i32 m0, s72, 0x2000
	s_nop 0
	global_load_lds_dwordx4 v144, s[28:29]
	s_mov_b32 m0, s12
	s_nop 0
	global_load_lds_dwordx4 v148, s[52:53]
	s_mov_b32 m0, s20
	s_nop 0
	global_load_lds_dwordx4 v146, s[52:53]
	s_waitcnt vmcnt(8)
	s_waitcnt lgkmcnt(0)
	s_barrier
	s_setprio 1
	s_waitcnt lgkmcnt(0)
	v_mfma_f32_16x16x32_bf16 v[60:63], v[64:67], v[180:183], v[60:63]
	v_mfma_f32_16x16x32_bf16 v[56:59], v[72:75], v[180:183], v[56:59]
	v_mfma_f32_16x16x32_bf16 v[44:47], v[64:67], v[188:191], v[44:47]
	v_mfma_f32_16x16x32_bf16 v[40:43], v[72:75], v[188:191], v[40:43]
	v_mfma_f32_16x16x32_bf16 v[28:31], v[64:67], v[200:203], v[28:31]
	v_mfma_f32_16x16x32_bf16 v[24:27], v[72:75], v[200:203], v[24:27]
	v_mfma_f32_16x16x32_bf16 v[12:15], v[64:67], v[208:211], v[12:15]
	v_mfma_f32_16x16x32_bf16 v[8:11], v[72:75], v[208:211], v[8:11]
	v_mfma_f32_16x16x32_bf16 v[60:63], v[68:71], v[184:187], v[60:63]
	v_mfma_f32_16x16x32_bf16 v[56:59], v[76:79], v[184:187], v[56:59]
	v_mfma_f32_16x16x32_bf16 v[44:47], v[68:71], v[196:199], v[44:47]
	v_mfma_f32_16x16x32_bf16 v[40:43], v[76:79], v[196:199], v[40:43]
	v_mfma_f32_16x16x32_bf16 v[28:31], v[68:71], v[204:207], v[28:31]
	v_mfma_f32_16x16x32_bf16 v[24:27], v[76:79], v[204:207], v[24:27]
	v_mfma_f32_16x16x32_bf16 v[12:15], v[68:71], v[222:225], v[12:15]
	v_mfma_f32_16x16x32_bf16 v[8:11], v[76:79], v[222:225], v[8:11]
	s_setprio 0
	s_setprio 1
	v_mfma_f32_16x16x32_bf16 v[52:55], v[156:159], v[180:183], v[52:55]
	v_mfma_f32_16x16x32_bf16 v[48:51], v[172:175], v[180:183], v[48:51]
	v_mfma_f32_16x16x32_bf16 v[36:39], v[156:159], v[188:191], v[36:39]
	v_mfma_f32_16x16x32_bf16 v[32:35], v[172:175], v[188:191], v[32:35]
	v_mfma_f32_16x16x32_bf16 v[20:23], v[156:159], v[200:203], v[20:23]
	v_mfma_f32_16x16x32_bf16 v[16:19], v[172:175], v[200:203], v[16:19]
	v_mfma_f32_16x16x32_bf16 v[4:7], v[156:159], v[208:211], v[4:7]
	v_mfma_f32_16x16x32_bf16 v[0:3], v[172:175], v[208:211], v[0:3]
	v_mfma_f32_16x16x32_bf16 v[52:55], v[168:171], v[184:187], v[52:55]
	v_mfma_f32_16x16x32_bf16 v[48:51], v[176:179], v[184:187], v[48:51]
	v_mfma_f32_16x16x32_bf16 v[36:39], v[168:171], v[196:199], v[36:39]
	v_mfma_f32_16x16x32_bf16 v[32:35], v[176:179], v[196:199], v[32:35]
	v_mfma_f32_16x16x32_bf16 v[20:23], v[168:171], v[204:207], v[20:23]
	v_mfma_f32_16x16x32_bf16 v[16:19], v[176:179], v[204:207], v[16:19]
	v_mfma_f32_16x16x32_bf16 v[4:7], v[168:171], v[222:225], v[4:7]
	v_mfma_f32_16x16x32_bf16 v[0:3], v[176:179], v[222:225], v[0:3]
	s_setprio 0
	s_barrier
; #define PG8_STAGE(bufoff, gbase, voff) do { _Pragma("unroll") for (int _i = 0; _i < 2; ++_i) \
;         __builtin_amdgcn_global_load_lds((const unsigned*)((const char*)(gbase) + (voff)[_i]), (PG8_LAS unsigned*)(lds + (bufoff) + ldsw + _i * 8192), 16, 0, 0); } while (0)
; #define PG8_LDA(dst, b, h) do { _Pragma("unroll") for (int m = 0; m < 4; ++m) _Pragma("unroll") for (int k = 0; k < 2; ++k) dst[m][k] = *(const PG8_LAS bf16x8*)(lds + PG8_SA(b, h) + aoff + m * 2048 + k * 1024); } while (0)
; #define PG8_LDB(dst, b, h) do { _Pragma("unroll") for (int n = 0; n < 2; ++n) _Pragma("unroll") for (int k = 0; k < 2; ++k) dst[n][k] = *(const PG8_LAS bf16x8*)(lds + PG8_SB(b, h) + boff + n * 2048 + k * 1024); } while (0)
; #define PG8_MMA(ai, bj, At, Bt) do { __builtin_amdgcn_s_setprio(1); _Pragma("unroll") for (int m = 0; m < 4; ++m) _Pragma("unroll") for (int n = 0; n < 2; ++n) _Pragma("unroll") for (int k = 0; k < 2; ++k) \
;         acc[ai][bj][m][n] = __builtin_amdgcn_mfma_f32_16x16x32_bf16(Bt[n][k], At[m][k], acc[ai][bj][m][n], 0, 0, 0); __builtin_amdgcn_s_setprio(0); } while (0)
; #define PG8_WAIT_V(n) asm volatile("s_waitcnt vmcnt(" #n ")" ::: "memory")
; #define PG8_WAIT_L(n) asm volatile("s_waitcnt lgkmcnt(" #n ")" ::: "memory")
; #define PG8_BAR __builtin_amdgcn_s_barrier()
; #define PG8_SCHED __builtin_amdgcn_sched_barrier(0)
; template <class Epi, class Sched, bool ALIGN_EPI = false, bool SP2 = false>
; __device__ __forceinline__ void gemm_phase(PG8_LAS unsigned char* lds, const Gemm g, const Sched& S, const Epi& E) {
;     ...
;         for (int t = 0; t < nt; t += 2) {
;             const bool last = (t == nt - 2);
;             const char* a1 = cA + (size_t)(t + 1) * kstep;
;             const char* a2 = last ? nA : cA + (size_t)(t + 2) * kstep; const char* b2 = last ? nB : cB + (size_t)(t + 2) * kstep;
;     ...
;             PG8_LDB(B0, 1, 0); PG8_LDB(B1, 1, 1); PG8_SCHED; PG8_LDA(At, 1, 0); PG8_STAGE(PG8_SA(0, 1), a2 + hstep, voffA);
;             PG8_WAIT_V(8); PG8_WAIT_L(0); PG8_BAR; PG8_MMA(0, 0, At, B0); PG8_MMA(0, 1, At, B1); PG8_BAR; PG8_SCHED;
;             PG8_LDA(At, 1, 1); PG8_STAGE(PG8_SB(1, 0), b3, voffB); PG8_STAGE(PG8_SB(1, 1), b3 + hstep, voffB); PG8_STAGE(PG8_SA(1, 0), a3, voffA);
;             PG8_WAIT_V(8); PG8_WAIT_L(0); PG8_BAR; PG8_MMA(1, 0, At, B0); PG8_MMA(1, 1, At, B1); PG8_BAR; PG8_SCHED;
	s_add_i32 s72, 0, 0x18000
	s_add_i32 s73, 0, 0x1c000
	ds_read_b128 v[64:67], v212
	ds_read_b128 v[68:71], v212 offset:1024
	ds_read_b128 v[72:75], v212 offset:2048
	ds_read_b128 v[76:79], v212 offset:3072
	ds_read_b128 v[156:159], v213
	ds_read_b128 v[168:171], v213 offset:1024
	ds_read_b128 v[172:175], v213 offset:2048
	ds_read_b128 v[176:179], v213 offset:3072
	s_add_u32 s28, s52, 0x80000
	s_addc_u32 s29, s53, 0
	s_mov_b32 m0, s21
	ds_read_b128 v[180:183], v165 offset:32768
	ds_read_b128 v[184:187], v165 offset:33792
	ds_read_b128 v[188:191], v165 offset:34816
	ds_read_b128 v[196:199], v165 offset:35840
	ds_read_b128 v[200:203], v165 offset:36864
	ds_read_b128 v[204:207], v165 offset:37888
	ds_read_b128 v[208:211], v165 offset:38912
	ds_read_b128 v[222:225], v165 offset:39936
	global_load_lds_dwordx4 v148, s[28:29]
	s_mov_b32 m0, s48
	s_nop 0
	global_load_lds_dwordx4 v146, s[28:29]
	s_waitcnt vmcnt(8)
	s_waitcnt lgkmcnt(0)
	s_barrier
	s_setprio 1
	s_waitcnt lgkmcnt(0)
	v_mfma_f32_16x16x32_bf16 v[140:143], v[64:67], v[180:183], v[140:143]
	v_mfma_f32_16x16x32_bf16 v[136:139], v[72:75], v[180:183], v[136:139]
	v_mfma_f32_16x16x32_bf16 v[124:127], v[64:67], v[188:191], v[124:127]
	v_mfma_f32_16x16x32_bf16 v[120:123], v[72:75], v[188:191], v[120:123]
	v_mfma_f32_16x16x32_bf16 v[108:111], v[64:67], v[200:203], v[108:111]
	v_mfma_f32_16x16x32_bf16 v[104:107], v[72:75], v[200:203], v[104:107]
	v_mfma_f32_16x16x32_bf16 v[92:95], v[64:67], v[208:211], v[92:95]
	v_mfma_f32_16x16x32_bf16 v[88:91], v[72:75], v[208:211], v[88:91]
	v_mfma_f32_16x16x32_bf16 v[140:143], v[68:71], v[184:187], v[140:143]
	v_mfma_f32_16x16x32_bf16 v[136:139], v[76:79], v[184:187], v[136:139]
	v_mfma_f32_16x16x32_bf16 v[124:127], v[68:71], v[196:199], v[124:127]
	v_mfma_f32_16x16x32_bf16 v[120:123], v[76:79], v[196:199], v[120:123]
	v_mfma_f32_16x16x32_bf16 v[108:111], v[68:71], v[204:207], v[108:111]
	v_mfma_f32_16x16x32_bf16 v[104:107], v[76:79], v[204:207], v[104:107]
	v_mfma_f32_16x16x32_bf16 v[92:95], v[68:71], v[222:225], v[92:95]
	v_mfma_f32_16x16x32_bf16 v[88:91], v[76:79], v[222:225], v[88:91]
	s_setprio 0
	s_setprio 1
	v_mfma_f32_16x16x32_bf16 v[132:135], v[156:159], v[180:183], v[132:135]
	v_mfma_f32_16x16x32_bf16 v[128:131], v[172:175], v[180:183], v[128:131]
	v_mfma_f32_16x16x32_bf16 v[116:119], v[156:159], v[188:191], v[116:119]
	v_mfma_f32_16x16x32_bf16 v[112:115], v[172:175], v[188:191], v[112:115]
	v_mfma_f32_16x16x32_bf16 v[100:103], v[156:159], v[200:203], v[100:103]
	v_mfma_f32_16x16x32_bf16 v[96:99], v[172:175], v[200:203], v[96:99]
	v_mfma_f32_16x16x32_bf16 v[84:87], v[156:159], v[208:211], v[84:87]
	v_mfma_f32_16x16x32_bf16 v[80:83], v[172:175], v[208:211], v[80:83]
	v_mfma_f32_16x16x32_bf16 v[132:135], v[168:171], v[184:187], v[132:135]
	v_mfma_f32_16x16x32_bf16 v[128:131], v[176:179], v[184:187], v[128:131]
	v_mfma_f32_16x16x32_bf16 v[116:119], v[168:171], v[196:199], v[116:119]
	v_mfma_f32_16x16x32_bf16 v[112:115], v[176:179], v[196:199], v[112:115]
	v_mfma_f32_16x16x32_bf16 v[100:103], v[168:171], v[204:207], v[100:103]
	v_mfma_f32_16x16x32_bf16 v[96:99], v[176:179], v[204:207], v[96:99]
	v_mfma_f32_16x16x32_bf16 v[84:87], v[168:171], v[222:225], v[84:87]
	v_mfma_f32_16x16x32_bf16 v[80:83], v[176:179], v[222:225], v[80:83]
	s_setprio 0
	s_barrier
	s_add_i32 s28, s72, s8
	s_add_u32 s98, s50, 0x80
	s_addc_u32 s99, s51, 0
	s_mov_b32 m0, s28
	ds_read_b128 v[180:183], v165 offset:49152
	ds_read_b128 v[184:187], v165 offset:50176
	ds_read_b128 v[188:191], v165 offset:51200
	ds_read_b128 v[196:199], v165 offset:52224
	ds_read_b128 v[200:203], v165 offset:53248
	ds_read_b128 v[204:207], v165 offset:54272
	ds_read_b128 v[208:211], v165 offset:55296
	ds_read_b128 v[222:225], v165 offset:56320
	global_load_lds_dwordx4 v194, s[98:99]
	s_add_i32 m0, s28, 0x2000
	s_add_u32 s28, s50, 0x80080
	s_addc_u32 s29, s51, 0
	s_add_i32 s50, s73, s8
	global_load_lds_dwordx4 v144, s[98:99]
	s_mov_b32 m0, s50
	s_add_u32 s100, s52, 0x80
	s_addc_u32 s101, s53, 0
	global_load_lds_dwordx4 v194, s[28:29]
	s_add_i32 m0, s50, 0x2000
	s_nop 0
	global_load_lds_dwordx4 v144, s[28:29]
	s_mov_b32 m0, s55
	s_nop 0
	global_load_lds_dwordx4 v148, s[100:101]
	s_mov_b32 m0, s60
	s_nop 0
	global_load_lds_dwordx4 v146, s[100:101]
	s_waitcnt vmcnt(8)
	s_waitcnt lgkmcnt(0)
	s_barrier
	s_setprio 1
	s_waitcnt lgkmcnt(0)
	v_mfma_f32_16x16x32_bf16 v[60:63], v[64:67], v[180:183], v[60:63]
	v_mfma_f32_16x16x32_bf16 v[56:59], v[72:75], v[180:183], v[56:59]
	v_mfma_f32_16x16x32_bf16 v[44:47], v[64:67], v[188:191], v[44:47]
	v_mfma_f32_16x16x32_bf16 v[40:43], v[72:75], v[188:191], v[40:43]
	v_mfma_f32_16x16x32_bf16 v[28:31], v[64:67], v[200:203], v[28:31]
	v_mfma_f32_16x16x32_bf16 v[24:27], v[72:75], v[200:203], v[24:27]
	v_mfma_f32_16x16x32_bf16 v[12:15], v[64:67], v[208:211], v[12:15]
	v_mfma_f32_16x16x32_bf16 v[8:11], v[72:75], v[208:211], v[8:11]
	v_mfma_f32_16x16x32_bf16 v[60:63], v[68:71], v[184:187], v[60:63]
	v_mfma_f32_16x16x32_bf16 v[56:59], v[76:79], v[184:187], v[56:59]
	v_mfma_f32_16x16x32_bf16 v[44:47], v[68:71], v[196:199], v[44:47]
	v_mfma_f32_16x16x32_bf16 v[40:43], v[76:79], v[196:199], v[40:43]
	v_mfma_f32_16x16x32_bf16 v[28:31], v[68:71], v[204:207], v[28:31]
	v_mfma_f32_16x16x32_bf16 v[24:27], v[76:79], v[204:207], v[24:27]
	v_mfma_f32_16x16x32_bf16 v[12:15], v[68:71], v[222:225], v[12:15]
	v_mfma_f32_16x16x32_bf16 v[8:11], v[76:79], v[222:225], v[8:11]
	s_setprio 0
	s_setprio 1
	v_mfma_f32_16x16x32_bf16 v[52:55], v[156:159], v[180:183], v[52:55]
	s_add_i32 s71, s71, 2
	v_mfma_f32_16x16x32_bf16 v[48:51], v[172:175], v[180:183], v[48:51]
	s_add_u32 s42, s42, 0x100
	v_mfma_f32_16x16x32_bf16 v[36:39], v[156:159], v[188:191], v[36:39]
	s_addc_u32 s43, s43, 0
	v_mfma_f32_16x16x32_bf16 v[32:35], v[172:175], v[188:191], v[32:35]
	s_add_u32 s67, s67, 0x100
	v_mfma_f32_16x16x32_bf16 v[20:23], v[156:159], v[200:203], v[20:23]
	s_addc_u32 s70, s70, 0
	v_mfma_f32_16x16x32_bf16 v[16:19], v[172:175], v[200:203], v[16:19]
	s_add_u32 s28, s42, 0xfff80080
	v_mfma_f32_16x16x32_bf16 v[4:7], v[156:159], v[208:211], v[4:7]
	s_addc_u32 s29, s43, -1
	v_mfma_f32_16x16x32_bf16 v[0:3], v[172:175], v[208:211], v[0:3]
	s_add_i32 s72, 0, 0x10000
	v_mfma_f32_16x16x32_bf16 v[52:55], v[168:171], v[184:187], v[52:55]
	s_cmp_eq_u32 s71, 28
	v_mfma_f32_16x16x32_bf16 v[48:51], v[176:179], v[184:187], v[48:51]
	s_cselect_b32 s53, s27, s29
	v_mfma_f32_16x16x32_bf16 v[36:39], v[168:171], v[196:199], v[36:39]
	s_cselect_b32 s52, s65, s28
	v_mfma_f32_16x16x32_bf16 v[32:35], v[176:179], v[196:199], v[32:35]
	s_cselect_b32 s51, s25, s70
	v_mfma_f32_16x16x32_bf16 v[20:23], v[168:171], v[204:207], v[20:23]
	s_cselect_b32 s50, s66, s67
	v_mfma_f32_16x16x32_bf16 v[16:19], v[176:179], v[204:207], v[16:19]
	s_add_i32 s73, 0, 0x14000
	v_mfma_f32_16x16x32_bf16 v[4:7], v[168:171], v[222:225], v[4:7]
	v_mfma_f32_16x16x32_bf16 v[0:3], v[176:179], v[222:225], v[0:3]
	s_setprio 0
	s_barrier
	s_cmp_gt_u32 s71, 29
	s_cbranch_scc0 .LBB0_55
	s_and_b64 vcc, exec, s[22:23]
	s_cbranch_vccz .LBB0_58
	s_barrier

; #define PG8_STAGE(bufoff, gbase, voff) do { _Pragma("unroll") for (int _i = 0; _i < 2; ++_i) \
;         __builtin_amdgcn_global_load_lds((const unsigned*)((const char*)(gbase) + (voff)[_i]), (PG8_LAS unsigned*)(lds + (bufoff) + ldsw + _i * 8192), 16, 0, 0); } while (0)
; #define PG8_LDA(dst, b, h) do { _Pragma("unroll") for (int m = 0; m < 4; ++m) _Pragma("unroll") for (int k = 0; k < 2; ++k) dst[m][k] = *(const PG8_LAS bf16x8*)(lds + PG8_SA(b, h) + aoff + m * 2048 + k * 1024); } while (0)
; #define PG8_LDB(dst, b, h) do { _Pragma("unroll") for (int n = 0; n < 2; ++n) _Pragma("unroll") for (int k = 0; k < 2; ++k) dst[n][k] = *(const PG8_LAS bf16x8*)(lds + PG8_SB(b, h) + boff + n * 2048 + k * 1024); } while (0)
; #define PG8_SCHED __builtin_amdgcn_sched_barrier(0)
; template <class Epi, class Sched, bool ALIGN_EPI = false, bool SP2 = false>
; __device__ __forceinline__ void gemm_phase(PG8_LAS unsigned char* lds, const Gemm g, const Sched& S, const Epi& E) {
;     ...
;         const bool has_next = S.next(ui + 1, nxt);
;         const char* nA = has_next ? (const char*)g.A + (size_t)nxt.pm * tstep : cA; const char* nB = has_next ? (const char*)g.Bt + (size_t)nxt.pn * tstep : cB;
;         for (int t = 0; t < nt; t += 2) {
;             const bool last = (t == nt - 2);
;             const char* a1 = cA + (size_t)(t + 1) * kstep;
;             const char* a2 = last ? nA : cA + (size_t)(t + 2) * kstep; const char* b2 = last ? nB : cB + (size_t)(t + 2) * kstep;
;             const char* a3 = a2 + kstep; const char* b3 = b2 + kstep;
;             if (last && has_next) S.a_ready(nxt);
;             if constexpr (SP2) {
;             PG8_LDB(B0, 0, 0); PG8_LDB(B1, 0, 1); PG8_SCHED; PG8_LDA(At, 0, 0); PG8_STAGE(PG8_SA(1, 1), a1 + hstep, voffA);
;     ...
; #pragma unroll
;         for (int a = 0; a < 2; ++a)
; #pragma unroll
;             for (int b = 0; b < 2; ++b)
; #pragma unroll
;                 for (int m = 0; m < 4; ++m)
; #pragma unroll
;                     for (int n = 0; n < 2; ++n) acc[a][b][m][n] = (f32x4){0.f, 0.f, 0.f, 0.f};
;         cur = nxt; cA = nA; cB = nB; ++ui;
.LBB0_401:
	s_ashr_i32 s61, s60, 31
	s_lshl_b64 s[28:29], s[60:61], 20
	s_add_u32 s66, s74, s28
	s_addc_u32 s67, s75, s29
	s_and_b64 s[28:29], s[44:45], exec
	s_cselect_b32 s50, s67, s27
	s_cselect_b32 s51, s66, s26
	s_ashr_i32 s55, s54, 31
	s_lshl_b64 s[28:29], s[54:55], 20
	s_add_u32 s64, s70, s28
	s_addc_u32 s65, s71, s29
	s_and_b64 s[28:29], s[44:45], exec
	s_cselect_b32 s52, s65, s47
	s_cselect_b32 s53, s64, s46
	s_add_u32 s26, s26, 0x80080
	s_addc_u32 s27, s27, 0
	s_add_u32 s55, s46, 0x100
	v_mov_b32_e32 v0, 0
	s_addc_u32 s61, s47, 0
	s_mov_b32 s88, -2
	v_mov_b32_e32 v1, v0
	v_mov_b32_e32 v2, v0
	v_mov_b32_e32 v3, v0
	v_mov_b32_e32 v4, v0
	v_mov_b32_e32 v5, v0
	v_mov_b32_e32 v6, v0
	v_mov_b32_e32 v7, v0
	v_mov_b32_e32 v16, v0
	v_mov_b32_e32 v17, v0
	v_mov_b32_e32 v18, v0
	v_mov_b32_e32 v19, v0
	v_mov_b32_e32 v20, v0
	s_waitcnt lgkmcnt(0)
	v_mov_b32_e32 v21, v0
	v_mov_b32_e32 v22, v0
	v_mov_b32_e32 v23, v0
	v_mov_b32_e32 v48, v0
	v_mov_b32_e32 v49, v0
	v_mov_b32_e32 v50, v0
	v_mov_b32_e32 v51, v0
	v_mov_b32_e32 v52, v0
	v_mov_b32_e32 v53, v0
	v_mov_b32_e32 v54, v0
	v_mov_b32_e32 v55, v0
	v_mov_b32_e32 v64, v0
	v_mov_b32_e32 v65, v0
	v_mov_b32_e32 v66, v0
	v_mov_b32_e32 v67, v0
	v_mov_b32_e32 v68, v0
	v_mov_b32_e32 v69, v0
	v_mov_b32_e32 v70, v0
	v_mov_b32_e32 v71, v0
	v_mov_b32_e32 v8, v0
	v_mov_b32_e32 v9, v0
	v_mov_b32_e32 v10, v0
	v_mov_b32_e32 v11, v0
	v_mov_b32_e32 v12, v0
	v_mov_b32_e32 v13, v0
	v_mov_b32_e32 v14, v0
	v_mov_b32_e32 v15, v0
	v_mov_b32_e32 v24, v0
	v_mov_b32_e32 v25, v0
	v_mov_b32_e32 v26, v0
	v_mov_b32_e32 v27, v0
	v_mov_b32_e32 v28, v0
	v_mov_b32_e32 v29, v0
	v_mov_b32_e32 v30, v0
	v_mov_b32_e32 v31, v0
	v_mov_b32_e32 v56, v0
	v_mov_b32_e32 v57, v0
	v_mov_b32_e32 v58, v0
	v_mov_b32_e32 v59, v0
	v_mov_b32_e32 v60, v0
	v_mov_b32_e32 v61, v0
	v_mov_b32_e32 v62, v0
	v_mov_b32_e32 v63, v0
	v_mov_b32_e32 v72, v0
	v_mov_b32_e32 v73, v0
	v_mov_b32_e32 v74, v0
	v_mov_b32_e32 v75, v0
	v_mov_b32_e32 v76, v0
	v_mov_b32_e32 v77, v0
	v_mov_b32_e32 v78, v0
	v_mov_b32_e32 v79, v0
	v_mov_b32_e32 v80, v0
	v_mov_b32_e32 v81, v0
	v_mov_b32_e32 v82, v0
	v_mov_b32_e32 v83, v0
	v_mov_b32_e32 v84, v0
	v_mov_b32_e32 v85, v0
	v_mov_b32_e32 v86, v0
	v_mov_b32_e32 v87, v0
	v_mov_b32_e32 v96, v0
	v_mov_b32_e32 v97, v0
	v_mov_b32_e32 v98, v0
	v_mov_b32_e32 v99, v0
	v_mov_b32_e32 v100, v0
	v_mov_b32_e32 v101, v0
	v_mov_b32_e32 v102, v0
	v_mov_b32_e32 v103, v0
	v_mov_b32_e32 v112, v0
	v_mov_b32_e32 v113, v0
	v_mov_b32_e32 v114, v0
	v_mov_b32_e32 v115, v0
	v_mov_b32_e32 v116, v0
	v_mov_b32_e32 v117, v0
	v_mov_b32_e32 v118, v0
	v_mov_b32_e32 v119, v0
	v_mov_b32_e32 v128, v0
	v_mov_b32_e32 v129, v0
	v_mov_b32_e32 v130, v0
	v_mov_b32_e32 v131, v0
	v_mov_b32_e32 v132, v0
	v_mov_b32_e32 v133, v0
	v_mov_b32_e32 v134, v0
	v_mov_b32_e32 v135, v0
	v_mov_b32_e32 v88, v0
	v_mov_b32_e32 v89, v0
	v_mov_b32_e32 v90, v0
	v_mov_b32_e32 v91, v0
	v_mov_b32_e32 v92, v0
	v_mov_b32_e32 v93, v0
	v_mov_b32_e32 v94, v0
	v_mov_b32_e32 v95, v0
	v_mov_b32_e32 v104, v0
	v_mov_b32_e32 v105, v0
	v_mov_b32_e32 v106, v0
	v_mov_b32_e32 v107, v0
	v_mov_b32_e32 v108, v0
	v_mov_b32_e32 v109, v0
	v_mov_b32_e32 v110, v0
	v_mov_b32_e32 v111, v0
	v_mov_b32_e32 v120, v0
	v_mov_b32_e32 v121, v0
	v_mov_b32_e32 v122, v0
	v_mov_b32_e32 v123, v0
	v_mov_b32_e32 v124, v0
	v_mov_b32_e32 v125, v0
	v_mov_b32_e32 v126, v0
	v_mov_b32_e32 v127, v0
	v_mov_b32_e32 v136, v0
	v_mov_b32_e32 v137, v0
	v_mov_b32_e32 v138, v0
	v_mov_b32_e32 v139, v0
	v_mov_b32_e32 v140, v0
	v_mov_b32_e32 v141, v0
	v_mov_b32_e32 v142, v0
	v_mov_b32_e32 v143, v0
	v_add_u32_e32 v192, 0x10000, v172
	v_add_u32_e32 v193, 0x14000, v172
	v_add_u32_e32 v212, 0x18000, v172
	v_add_u32_e32 v213, 0x1c000, v172
	s_add_u32 s28, s26, 0xfff80080
	s_addc_u32 s29, s27, -1
	s_add_i32 s72, 0, 0x10000
	s_cmp_eq_u32 s88, 28
	s_cselect_b32 s49, s50, s29
	s_cselect_b32 s48, s51, s28
	s_cselect_b32 s47, s52, s61
	s_cselect_b32 s46, s53, s55
	s_add_i32 s73, 0, 0x14000
.LBB0_402:
	ds_read_b128 v[32:35], v192
	ds_read_b128 v[36:39], v192 offset:1024
	ds_read_b128 v[40:43], v192 offset:2048
	ds_read_b128 v[44:47], v192 offset:3072
	ds_read_b128 v[160:163], v193
	ds_read_b128 v[164:167], v193 offset:1024
	ds_read_b128 v[168:171], v193 offset:2048
	ds_read_b128 v[176:179], v193 offset:3072
	s_add_i32 m0, s77, 0xc000
	ds_read_b128 v[180:183], v174
	ds_read_b128 v[184:187], v174 offset:1024
	ds_read_b128 v[188:191], v174 offset:2048
	ds_read_b128 v[196:199], v174 offset:3072
	ds_read_b128 v[200:203], v174 offset:4096
	ds_read_b128 v[204:207], v174 offset:5120
	ds_read_b128 v[208:211], v174 offset:6144
	ds_read_b128 v[234:237], v174 offset:7168
	global_load_lds_dwordx4 v156, s[26:27]
	s_add_i32 m0, s77, 0xe000
	s_nop 0
	global_load_lds_dwordx4 v158, s[26:27]
	s_waitcnt vmcnt(8)
	s_waitcnt lgkmcnt(0)
	s_barrier
; #define PG8_STAGE(bufoff, gbase, voff) do { _Pragma("unroll") for (int _i = 0; _i < 2; ++_i) \
;         __builtin_amdgcn_global_load_lds((const unsigned*)((const char*)(gbase) + (voff)[_i]), (PG8_LAS unsigned*)(lds + (bufoff) + ldsw + _i * 8192), 16, 0, 0); } while (0)
; #define PG8_LDA(dst, b, h) do { _Pragma("unroll") for (int m = 0; m < 4; ++m) _Pragma("unroll") for (int k = 0; k < 2; ++k) dst[m][k] = *(const PG8_LAS bf16x8*)(lds + PG8_SA(b, h) + aoff + m * 2048 + k * 1024); } while (0)
; #define PG8_LDB(dst, b, h) do { _Pragma("unroll") for (int n = 0; n < 2; ++n) _Pragma("unroll") for (int k = 0; k < 2; ++k) dst[n][k] = *(const PG8_LAS bf16x8*)(lds + PG8_SB(b, h) + boff + n * 2048 + k * 1024); } while (0)
; #define PG8_MMA(ai, bj, At, Bt) do { __builtin_amdgcn_s_setprio(1); _Pragma("unroll") for (int m = 0; m < 4; ++m) _Pragma("unroll") for (int n = 0; n < 2; ++n) _Pragma("unroll") for (int k = 0; k < 2; ++k) \
;         acc[ai][bj][m][n] = __builtin_amdgcn_mfma_f32_16x16x32_bf16(Bt[n][k], At[m][k], acc[ai][bj][m][n], 0, 0, 0); __builtin_amdgcn_s_setprio(0); } while (0)
; #define PG8_WAIT_V(n) asm volatile("s_waitcnt vmcnt(" #n ")" ::: "memory")
; #define PG8_WAIT_L(n) asm volatile("s_waitcnt lgkmcnt(" #n ")" ::: "memory")
; #define PG8_BAR __builtin_amdgcn_s_barrier()
; #define PG8_SCHED __builtin_amdgcn_sched_barrier(0)
; template <class Epi, class Sched, bool ALIGN_EPI = false, bool SP2 = false>
; __device__ __forceinline__ void gemm_phase(PG8_LAS unsigned char* lds, const Gemm g, const Sched& S, const Epi& E) {
;     ...
;             PG8_LDB(B0, 0, 0); PG8_LDB(B1, 0, 1); PG8_SCHED; PG8_LDA(At, 0, 0); PG8_STAGE(PG8_SA(1, 1), a1 + hstep, voffA);
;             PG8_WAIT_V(8); PG8_WAIT_L(0); PG8_BAR; PG8_MMA(0, 0, At, B0); PG8_MMA(0, 1, At, B1); PG8_BAR; PG8_SCHED;
;             PG8_LDA(At, 0, 1); PG8_STAGE(PG8_SB(0, 0), b2, voffB); PG8_STAGE(PG8_SB(0, 1), b2 + hstep, voffB); PG8_STAGE(PG8_SA(0, 0), a2, voffA);
;             PG8_WAIT_V(8); PG8_WAIT_L(0); PG8_BAR; PG8_MMA(1, 0, At, B0); PG8_MMA(1, 1, At, B1); PG8_BAR; PG8_SCHED;
	s_setprio 1
	s_waitcnt lgkmcnt(0)
	v_mfma_f32_16x16x32_bf16 v[140:143], v[32:35], v[180:183], v[140:143]
	v_mfma_f32_16x16x32_bf16 v[136:139], v[40:43], v[180:183], v[136:139]
	v_mfma_f32_16x16x32_bf16 v[124:127], v[32:35], v[188:191], v[124:127]
	v_mfma_f32_16x16x32_bf16 v[120:123], v[40:43], v[188:191], v[120:123]
	v_mfma_f32_16x16x32_bf16 v[108:111], v[32:35], v[200:203], v[108:111]
	v_mfma_f32_16x16x32_bf16 v[104:107], v[40:43], v[200:203], v[104:107]
	v_mfma_f32_16x16x32_bf16 v[92:95], v[32:35], v[208:211], v[92:95]
	v_mfma_f32_16x16x32_bf16 v[88:91], v[40:43], v[208:211], v[88:91]
	v_mfma_f32_16x16x32_bf16 v[140:143], v[36:39], v[184:187], v[140:143]
	v_mfma_f32_16x16x32_bf16 v[136:139], v[44:47], v[184:187], v[136:139]
	v_mfma_f32_16x16x32_bf16 v[124:127], v[36:39], v[196:199], v[124:127]
	v_mfma_f32_16x16x32_bf16 v[120:123], v[44:47], v[196:199], v[120:123]
	v_mfma_f32_16x16x32_bf16 v[108:111], v[36:39], v[204:207], v[108:111]
	v_mfma_f32_16x16x32_bf16 v[104:107], v[44:47], v[204:207], v[104:107]
	v_mfma_f32_16x16x32_bf16 v[92:95], v[36:39], v[234:237], v[92:95]
	v_mfma_f32_16x16x32_bf16 v[88:91], v[44:47], v[234:237], v[88:91]
	s_setprio 0
	s_setprio 1
	v_mfma_f32_16x16x32_bf16 v[132:135], v[160:163], v[180:183], v[132:135]
	v_mfma_f32_16x16x32_bf16 v[128:131], v[168:171], v[180:183], v[128:131]
	v_mfma_f32_16x16x32_bf16 v[116:119], v[160:163], v[188:191], v[116:119]
	v_mfma_f32_16x16x32_bf16 v[112:115], v[168:171], v[188:191], v[112:115]
	v_mfma_f32_16x16x32_bf16 v[100:103], v[160:163], v[200:203], v[100:103]
	v_mfma_f32_16x16x32_bf16 v[96:99], v[168:171], v[200:203], v[96:99]
	v_mfma_f32_16x16x32_bf16 v[84:87], v[160:163], v[208:211], v[84:87]
	v_mfma_f32_16x16x32_bf16 v[80:83], v[168:171], v[208:211], v[80:83]
	v_mfma_f32_16x16x32_bf16 v[132:135], v[164:167], v[184:187], v[132:135]
	v_mfma_f32_16x16x32_bf16 v[128:131], v[176:179], v[184:187], v[128:131]
	v_mfma_f32_16x16x32_bf16 v[116:119], v[164:167], v[196:199], v[116:119]
	v_mfma_f32_16x16x32_bf16 v[112:115], v[176:179], v[196:199], v[112:115]
	v_mfma_f32_16x16x32_bf16 v[100:103], v[164:167], v[204:207], v[100:103]
	v_mfma_f32_16x16x32_bf16 v[96:99], v[176:179], v[204:207], v[96:99]
	v_mfma_f32_16x16x32_bf16 v[84:87], v[164:167], v[234:237], v[84:87]
	v_mfma_f32_16x16x32_bf16 v[80:83], v[176:179], v[234:237], v[80:83]
	s_setprio 0
	s_barrier
	s_add_i32 s28, s72, s76
	s_mov_b32 m0, s28
	ds_read_b128 v[180:183], v174 offset:16384
	ds_read_b128 v[184:187], v174 offset:17408
	ds_read_b128 v[188:191], v174 offset:18432
	ds_read_b128 v[196:199], v174 offset:19456
	ds_read_b128 v[200:203], v174 offset:20480
	ds_read_b128 v[204:207], v174 offset:21504
	ds_read_b128 v[208:211], v174 offset:22528
	ds_read_b128 v[234:237], v174 offset:23552
	global_load_lds_dwordx4 v148, s[46:47]
	s_add_i32 m0, s28, 0x2000
	s_add_u32 s28, s46, 0x80000
	s_addc_u32 s29, s47, 0
	s_add_i32 s72, s73, s76
	global_load_lds_dwordx4 v144, s[46:47]
	s_mov_b32 m0, s72
	s_nop 0
	global_load_lds_dwordx4 v148, s[28:29]
	s_add_i32 m0, s72, 0x2000
	s_nop 0
	global_load_lds_dwordx4 v144, s[28:29]
	s_mov_b32 m0, s77
	s_nop 0
	global_load_lds_dwordx4 v150, s[48:49]
	s_mov_b32 m0, s79
	s_nop 0
	global_load_lds_dwordx4 v146, s[48:49]
	s_waitcnt vmcnt(8)
	s_waitcnt lgkmcnt(0)
	s_barrier
	s_setprio 1
	s_waitcnt lgkmcnt(0)
	v_mfma_f32_16x16x32_bf16 v[76:79], v[32:35], v[180:183], v[76:79]
	v_mfma_f32_16x16x32_bf16 v[72:75], v[40:43], v[180:183], v[72:75]
	v_mfma_f32_16x16x32_bf16 v[60:63], v[32:35], v[188:191], v[60:63]
	v_mfma_f32_16x16x32_bf16 v[56:59], v[40:43], v[188:191], v[56:59]
	v_mfma_f32_16x16x32_bf16 v[28:31], v[32:35], v[200:203], v[28:31]
	v_mfma_f32_16x16x32_bf16 v[24:27], v[40:43], v[200:203], v[24:27]
	v_mfma_f32_16x16x32_bf16 v[12:15], v[32:35], v[208:211], v[12:15]
	v_mfma_f32_16x16x32_bf16 v[8:11], v[40:43], v[208:211], v[8:11]
	v_mfma_f32_16x16x32_bf16 v[76:79], v[36:39], v[184:187], v[76:79]
	v_mfma_f32_16x16x32_bf16 v[72:75], v[44:47], v[184:187], v[72:75]
	v_mfma_f32_16x16x32_bf16 v[60:63], v[36:39], v[196:199], v[60:63]
	v_mfma_f32_16x16x32_bf16 v[56:59], v[44:47], v[196:199], v[56:59]
	v_mfma_f32_16x16x32_bf16 v[28:31], v[36:39], v[204:207], v[28:31]
	v_mfma_f32_16x16x32_bf16 v[24:27], v[44:47], v[204:207], v[24:27]
	v_mfma_f32_16x16x32_bf16 v[12:15], v[36:39], v[234:237], v[12:15]
	v_mfma_f32_16x16x32_bf16 v[8:11], v[44:47], v[234:237], v[8:11]
	s_setprio 0
	s_setprio 1
	v_mfma_f32_16x16x32_bf16 v[20:23], v[160:163], v[200:203], v[20:23]
	v_mfma_f32_16x16x32_bf16 v[16:19], v[168:171], v[200:203], v[16:19]
	v_mfma_f32_16x16x32_bf16 v[4:7], v[160:163], v[208:211], v[4:7]
	v_mfma_f32_16x16x32_bf16 v[0:3], v[168:171], v[208:211], v[0:3]
	v_mfma_f32_16x16x32_bf16 v[32:35], v[160:163], v[180:183], v[68:71]
	v_mfma_f32_16x16x32_bf16 v[36:39], v[168:171], v[180:183], v[64:67]
	v_mfma_f32_16x16x32_bf16 v[40:43], v[160:163], v[188:191], v[52:55]
	v_mfma_f32_16x16x32_bf16 v[44:47], v[168:171], v[188:191], v[48:51]
	v_mfma_f32_16x16x32_bf16 v[20:23], v[164:167], v[204:207], v[20:23]
	v_mfma_f32_16x16x32_bf16 v[16:19], v[176:179], v[204:207], v[16:19]
	v_mfma_f32_16x16x32_bf16 v[4:7], v[164:167], v[234:237], v[4:7]
	v_mfma_f32_16x16x32_bf16 v[0:3], v[176:179], v[234:237], v[0:3]
	v_mfma_f32_16x16x32_bf16 v[32:35], v[164:167], v[184:187], v[32:35]
	v_mfma_f32_16x16x32_bf16 v[36:39], v[176:179], v[184:187], v[36:39]
	v_mfma_f32_16x16x32_bf16 v[40:43], v[164:167], v[196:199], v[40:43]
	v_mfma_f32_16x16x32_bf16 v[44:47], v[176:179], v[196:199], v[44:47]
	s_setprio 0
	s_barrier
; #define PG8_STAGE(bufoff, gbase, voff) do { _Pragma("unroll") for (int _i = 0; _i < 2; ++_i) \
;         __builtin_amdgcn_global_load_lds((const unsigned*)((const char*)(gbase) + (voff)[_i]), (PG8_LAS unsigned*)(lds + (bufoff) + ldsw + _i * 8192), 16, 0, 0); } while (0)
; #define PG8_LDA(dst, b, h) do { _Pragma("unroll") for (int m = 0; m < 4; ++m) _Pragma("unroll") for (int k = 0; k < 2; ++k) dst[m][k] = *(const PG8_LAS bf16x8*)(lds + PG8_SA(b, h) + aoff + m * 2048 + k * 1024); } while (0)
; #define PG8_LDB(dst, b, h) do { _Pragma("unroll") for (int n = 0; n < 2; ++n) _Pragma("unroll") for (int k = 0; k < 2; ++k) dst[n][k] = *(const PG8_LAS bf16x8*)(lds + PG8_SB(b, h) + boff + n * 2048 + k * 1024); } while (0)
; #define PG8_MMA(ai, bj, At, Bt) do { __builtin_amdgcn_s_setprio(1); _Pragma("unroll") for (int m = 0; m < 4; ++m) _Pragma("unroll") for (int n = 0; n < 2; ++n) _Pragma("unroll") for (int k = 0; k < 2; ++k) \
;         acc[ai][bj][m][n] = __builtin_amdgcn_mfma_f32_16x16x32_bf16(Bt[n][k], At[m][k], acc[ai][bj][m][n], 0, 0, 0); __builtin_amdgcn_s_setprio(0); } while (0)
; #define PG8_WAIT_V(n) asm volatile("s_waitcnt vmcnt(" #n ")" ::: "memory")
; #define PG8_WAIT_L(n) asm volatile("s_waitcnt lgkmcnt(" #n ")" ::: "memory")
; #define PG8_BAR __builtin_amdgcn_s_barrier()
; #define PG8_SCHED __builtin_amdgcn_sched_barrier(0)
; template <class Epi, class Sched, bool ALIGN_EPI = false, bool SP2 = false>
; __device__ __forceinline__ void gemm_phase(PG8_LAS unsigned char* lds, const Gemm g, const Sched& S, const Epi& E) {
;     ...
;         for (int t = 0; t < nt; t += 2) {
;             const bool last = (t == nt - 2);
;             const char* a1 = cA + (size_t)(t + 1) * kstep;
;             const char* a2 = last ? nA : cA + (size_t)(t + 2) * kstep; const char* b2 = last ? nB : cB + (size_t)(t + 2) * kstep;
;     ...
;             PG8_LDB(B0, 1, 0); PG8_LDB(B1, 1, 1); PG8_SCHED; PG8_LDA(At, 1, 0); PG8_STAGE(PG8_SA(0, 1), a2 + hstep, voffA);
;             PG8_WAIT_V(8); PG8_WAIT_L(0); PG8_BAR; PG8_MMA(0, 0, At, B0); PG8_MMA(0, 1, At, B1); PG8_BAR; PG8_SCHED;
;             PG8_LDA(At, 1, 1); PG8_STAGE(PG8_SB(1, 0), b3, voffB); PG8_STAGE(PG8_SB(1, 1), b3 + hstep, voffB); PG8_STAGE(PG8_SA(1, 0), a3, voffA);
;             PG8_WAIT_V(8); PG8_WAIT_L(0); PG8_BAR; PG8_MMA(1, 0, At, B0); PG8_MMA(1, 1, At, B1); PG8_BAR; PG8_SCHED;
	s_add_i32 s72, 0, 0x18000
	s_add_i32 s73, 0, 0x1c000
	ds_read_b128 v[48:51], v212
	ds_read_b128 v[52:55], v212 offset:1024
	ds_read_b128 v[64:67], v212 offset:2048
	ds_read_b128 v[68:71], v212 offset:3072
	ds_read_b128 v[160:163], v213
	ds_read_b128 v[164:167], v213 offset:1024
	ds_read_b128 v[168:171], v213 offset:2048
	ds_read_b128 v[176:179], v213 offset:3072
	s_add_u32 s28, s48, 0x80000
	s_addc_u32 s29, s49, 0
	s_mov_b32 m0, s80
	ds_read_b128 v[180:183], v174 offset:32768
	ds_read_b128 v[184:187], v174 offset:33792
	ds_read_b128 v[188:191], v174 offset:34816
	ds_read_b128 v[196:199], v174 offset:35840
	ds_read_b128 v[200:203], v174 offset:36864
	ds_read_b128 v[204:207], v174 offset:37888
	ds_read_b128 v[208:211], v174 offset:38912
	ds_read_b128 v[234:237], v174 offset:39936
	global_load_lds_dwordx4 v150, s[28:29]
	s_mov_b32 m0, s12
	s_nop 0
	global_load_lds_dwordx4 v146, s[28:29]
	s_waitcnt vmcnt(8)
	s_waitcnt lgkmcnt(0)
	s_barrier
	s_setprio 1
	s_waitcnt lgkmcnt(0)
	v_mfma_f32_16x16x32_bf16 v[140:143], v[48:51], v[180:183], v[140:143]
	v_mfma_f32_16x16x32_bf16 v[136:139], v[64:67], v[180:183], v[136:139]
	v_mfma_f32_16x16x32_bf16 v[124:127], v[48:51], v[188:191], v[124:127]
	v_mfma_f32_16x16x32_bf16 v[120:123], v[64:67], v[188:191], v[120:123]
	v_mfma_f32_16x16x32_bf16 v[108:111], v[48:51], v[200:203], v[108:111]
	v_mfma_f32_16x16x32_bf16 v[104:107], v[64:67], v[200:203], v[104:107]
	v_mfma_f32_16x16x32_bf16 v[92:95], v[48:51], v[208:211], v[92:95]
	v_mfma_f32_16x16x32_bf16 v[88:91], v[64:67], v[208:211], v[88:91]
	v_mfma_f32_16x16x32_bf16 v[140:143], v[52:55], v[184:187], v[140:143]
	v_mfma_f32_16x16x32_bf16 v[136:139], v[68:71], v[184:187], v[136:139]
	v_mfma_f32_16x16x32_bf16 v[124:127], v[52:55], v[196:199], v[124:127]
	v_mfma_f32_16x16x32_bf16 v[120:123], v[68:71], v[196:199], v[120:123]
	v_mfma_f32_16x16x32_bf16 v[108:111], v[52:55], v[204:207], v[108:111]
	v_mfma_f32_16x16x32_bf16 v[104:107], v[68:71], v[204:207], v[104:107]
	v_mfma_f32_16x16x32_bf16 v[92:95], v[52:55], v[234:237], v[92:95]
	v_mfma_f32_16x16x32_bf16 v[88:91], v[68:71], v[234:237], v[88:91]
	s_setprio 0
	s_setprio 1
	v_mfma_f32_16x16x32_bf16 v[132:135], v[160:163], v[180:183], v[132:135]
	v_mfma_f32_16x16x32_bf16 v[128:131], v[168:171], v[180:183], v[128:131]
	v_mfma_f32_16x16x32_bf16 v[116:119], v[160:163], v[188:191], v[116:119]
	v_mfma_f32_16x16x32_bf16 v[112:115], v[168:171], v[188:191], v[112:115]
	v_mfma_f32_16x16x32_bf16 v[100:103], v[160:163], v[200:203], v[100:103]
	v_mfma_f32_16x16x32_bf16 v[96:99], v[168:171], v[200:203], v[96:99]
	v_mfma_f32_16x16x32_bf16 v[84:87], v[160:163], v[208:211], v[84:87]
	v_mfma_f32_16x16x32_bf16 v[80:83], v[168:171], v[208:211], v[80:83]
	v_mfma_f32_16x16x32_bf16 v[132:135], v[164:167], v[184:187], v[132:135]
	v_mfma_f32_16x16x32_bf16 v[128:131], v[176:179], v[184:187], v[128:131]
	v_mfma_f32_16x16x32_bf16 v[116:119], v[164:167], v[196:199], v[116:119]
	v_mfma_f32_16x16x32_bf16 v[112:115], v[176:179], v[196:199], v[112:115]
	v_mfma_f32_16x16x32_bf16 v[100:103], v[164:167], v[204:207], v[100:103]
	v_mfma_f32_16x16x32_bf16 v[96:99], v[176:179], v[204:207], v[96:99]
	v_mfma_f32_16x16x32_bf16 v[84:87], v[164:167], v[234:237], v[84:87]
	v_mfma_f32_16x16x32_bf16 v[80:83], v[176:179], v[234:237], v[80:83]
	s_setprio 0
	s_barrier
	s_add_i32 s28, s72, s76
	s_add_u32 s98, s46, 0x80
	s_addc_u32 s99, s47, 0
	s_mov_b32 m0, s28
	ds_read_b128 v[180:183], v174 offset:49152
	ds_read_b128 v[184:187], v174 offset:50176
	ds_read_b128 v[188:191], v174 offset:51200
	ds_read_b128 v[196:199], v174 offset:52224
	ds_read_b128 v[200:203], v174 offset:53248
	ds_read_b128 v[204:207], v174 offset:54272
	ds_read_b128 v[208:211], v174 offset:55296
	ds_read_b128 v[234:237], v174 offset:56320
	global_load_lds_dwordx4 v148, s[98:99]
	s_add_i32 m0, s28, 0x2000
	s_add_u32 s28, s46, 0x80080
	s_addc_u32 s29, s47, 0
	s_add_i32 s46, s73, s76
	global_load_lds_dwordx4 v144, s[98:99]
	s_mov_b32 m0, s46
	s_add_u32 s100, s48, 0x80
	s_addc_u32 s101, s49, 0
	global_load_lds_dwordx4 v148, s[28:29]
	s_add_i32 m0, s46, 0x2000
	s_nop 0
	global_load_lds_dwordx4 v144, s[28:29]
	s_mov_b32 m0, s78
	s_nop 0
	global_load_lds_dwordx4 v150, s[100:101]
	s_mov_b32 m0, s86
	s_nop 0
	global_load_lds_dwordx4 v146, s[100:101]
	s_waitcnt vmcnt(8)
	s_waitcnt lgkmcnt(0)
	s_barrier
	s_setprio 1
	s_waitcnt lgkmcnt(0)
	v_mfma_f32_16x16x32_bf16 v[76:79], v[48:51], v[180:183], v[76:79]
	v_mfma_f32_16x16x32_bf16 v[72:75], v[64:67], v[180:183], v[72:75]
	v_mfma_f32_16x16x32_bf16 v[60:63], v[48:51], v[188:191], v[60:63]
	v_mfma_f32_16x16x32_bf16 v[56:59], v[64:67], v[188:191], v[56:59]
	v_mfma_f32_16x16x32_bf16 v[28:31], v[48:51], v[200:203], v[28:31]
	v_mfma_f32_16x16x32_bf16 v[24:27], v[64:67], v[200:203], v[24:27]
	v_mfma_f32_16x16x32_bf16 v[12:15], v[48:51], v[208:211], v[12:15]
	v_mfma_f32_16x16x32_bf16 v[8:11], v[64:67], v[208:211], v[8:11]
	v_mfma_f32_16x16x32_bf16 v[76:79], v[52:55], v[184:187], v[76:79]
	v_mfma_f32_16x16x32_bf16 v[72:75], v[68:71], v[184:187], v[72:75]
	v_mfma_f32_16x16x32_bf16 v[60:63], v[52:55], v[196:199], v[60:63]
	v_mfma_f32_16x16x32_bf16 v[56:59], v[68:71], v[196:199], v[56:59]
	v_mfma_f32_16x16x32_bf16 v[28:31], v[52:55], v[204:207], v[28:31]
	v_mfma_f32_16x16x32_bf16 v[24:27], v[68:71], v[204:207], v[24:27]
	v_mfma_f32_16x16x32_bf16 v[12:15], v[52:55], v[234:237], v[12:15]
	v_mfma_f32_16x16x32_bf16 v[8:11], v[68:71], v[234:237], v[8:11]
	s_setprio 0
	s_setprio 1
	v_mfma_f32_16x16x32_bf16 v[32:35], v[160:163], v[180:183], v[32:35]
	s_add_i32 s88, s88, 2
	v_mfma_f32_16x16x32_bf16 v[68:71], v[164:167], v[184:187], v[32:35]
	s_add_u32 s26, s26, 0x100
	v_mfma_f32_16x16x32_bf16 v[32:35], v[168:171], v[180:183], v[36:39]
	s_addc_u32 s27, s27, 0
	v_mfma_f32_16x16x32_bf16 v[64:67], v[176:179], v[184:187], v[32:35]
	s_add_u32 s55, s55, 0x100
	v_mfma_f32_16x16x32_bf16 v[32:35], v[160:163], v[188:191], v[40:43]
	s_addc_u32 s61, s61, 0
	v_mfma_f32_16x16x32_bf16 v[52:55], v[164:167], v[196:199], v[32:35]
	s_add_u32 s28, s26, 0xfff80080
	v_mfma_f32_16x16x32_bf16 v[32:35], v[168:171], v[188:191], v[44:47]
	s_addc_u32 s29, s27, -1
	v_mfma_f32_16x16x32_bf16 v[20:23], v[160:163], v[200:203], v[20:23]
	s_add_i32 s72, 0, 0x10000
	v_mfma_f32_16x16x32_bf16 v[16:19], v[168:171], v[200:203], v[16:19]
	s_cmp_eq_u32 s88, 28
	v_mfma_f32_16x16x32_bf16 v[4:7], v[160:163], v[208:211], v[4:7]
	s_cselect_b32 s49, s50, s29
	v_mfma_f32_16x16x32_bf16 v[0:3], v[168:171], v[208:211], v[0:3]
	s_cselect_b32 s48, s51, s28
	v_mfma_f32_16x16x32_bf16 v[48:51], v[176:179], v[196:199], v[32:35]
	s_cselect_b32 s47, s52, s61
	v_mfma_f32_16x16x32_bf16 v[20:23], v[164:167], v[204:207], v[20:23]
	s_cselect_b32 s46, s53, s55
	v_mfma_f32_16x16x32_bf16 v[16:19], v[176:179], v[204:207], v[16:19]
	s_add_i32 s73, 0, 0x14000
	v_mfma_f32_16x16x32_bf16 v[4:7], v[164:167], v[234:237], v[4:7]
	v_mfma_f32_16x16x32_bf16 v[0:3], v[176:179], v[234:237], v[0:3]
	s_setprio 0
	s_barrier
	s_cmp_gt_u32 s88, 29
	s_cbranch_scc0 .LBB0_402
	s_and_b64 vcc, exec, s[22:23]
	s_cbranch_vccz .LBB0_405
	s_barrier
